# attention ring loops: folded 16 canonicalising v_max_f32 x,x into the consuming max (identical for non-NaN values)
# speedup vs baseline: 1.0058x; 1.0007x over previous
.LBB0_1158:
	v_max_f32_e32 v108, v34, v35
	v_max3_f32 v108, v108, v36, v37
	v_max3_f32 v108, v108, v38, v39
	v_max3_f32 v108, v108, v40, v41
	v_max3_f32 v108, v108, v42, v43
	v_max3_f32 v108, v108, v44, v45
	v_max3_f32 v108, v108, v46, v47
	v_max3_f32 v108, v108, v48, v49
	v_max3_f32 v108, v108, v50, v51
	v_max3_f32 v108, v108, v52, v53
	v_max3_f32 v108, v108, v54, v55
	v_max3_f32 v108, v108, v56, v57
	v_max3_f32 v108, v108, v58, v59
	v_max3_f32 v108, v108, v60, v61
	v_max3_f32 v108, v108, v62, v63
	v_max3_f32 v108, v108, v64, v65
	ds_bpermute_b32 v110, v209, v108
	v_sub_co_u32_e64 v111, vcc, s42, 32
	v_lshrrev_b32_e32 v0, s42, v102
	v_lshrrev_b32_e32 v111, v111, v103
	v_cndmask_b32_e32 v0, v111, v0, vcc
	v_and_b32_e32 v0, 1, v0
	s_waitcnt lgkmcnt(0)
	v_max_f32_e32 v108, v108, v110
	v_cmp_eq_u32_e64 s[2:3], 0, v0
	s_nop 1
	v_cndmask_b32_e64 v0, v108, v196, s[2:3]
	v_max_f32_e32 v117, v116, v0
	v_sub_f32_e32 v0, v116, v117
	v_exp_f32_e32 v108, v0
	s_nop 0
	v_cmp_neq_f32_e32 vcc, 1.0, v108
	s_cbranch_vccz .LBB0_1160
	v_pk_mul_f32 v[32:33], v[32:33], v[108:109] op_sel_hi:[1,0]
	v_pk_mul_f32 v[30:31], v[30:31], v[108:109] op_sel_hi:[1,0]
	v_pk_mul_f32 v[28:29], v[28:29], v[108:109] op_sel_hi:[1,0]
	v_pk_mul_f32 v[26:27], v[26:27], v[108:109] op_sel_hi:[1,0]
	v_pk_mul_f32 v[24:25], v[24:25], v[108:109] op_sel_hi:[1,0]
	v_pk_mul_f32 v[22:23], v[22:23], v[108:109] op_sel_hi:[1,0]
	v_pk_mul_f32 v[20:21], v[20:21], v[108:109] op_sel_hi:[1,0]
	v_pk_mul_f32 v[18:19], v[18:19], v[108:109] op_sel_hi:[1,0]
	v_pk_mul_f32 v[16:17], v[16:17], v[108:109] op_sel_hi:[1,0]
	v_pk_mul_f32 v[14:15], v[14:15], v[108:109] op_sel_hi:[1,0]
	v_pk_mul_f32 v[12:13], v[12:13], v[108:109] op_sel_hi:[1,0]
	v_pk_mul_f32 v[10:11], v[10:11], v[108:109] op_sel_hi:[1,0]
	v_pk_mul_f32 v[8:9], v[8:9], v[108:109] op_sel_hi:[1,0]
	v_pk_mul_f32 v[6:7], v[6:7], v[108:109] op_sel_hi:[1,0]
	v_pk_mul_f32 v[4:5], v[4:5], v[108:109] op_sel_hi:[1,0]
	v_pk_mul_f32 v[2:3], v[2:3], v[108:109] op_sel_hi:[1,0]

.LBB0_1171:
	v_max_f32_e32 v108, v66, v67
	v_max3_f32 v108, v108, v68, v69
	v_max3_f32 v108, v108, v70, v71
	v_max3_f32 v108, v108, v72, v73
	v_max3_f32 v108, v108, v74, v75
	v_max3_f32 v108, v108, v76, v77
	v_max3_f32 v108, v108, v78, v79
	v_max3_f32 v108, v108, v80, v81
	v_max3_f32 v108, v108, v82, v83
	v_max3_f32 v108, v108, v84, v85
	v_max3_f32 v108, v108, v86, v87
	v_max3_f32 v108, v108, v88, v89
	v_max3_f32 v108, v108, v90, v91
	v_max3_f32 v108, v108, v92, v93
	v_max3_f32 v108, v108, v94, v95
	v_max3_f32 v108, v108, v96, v97
	ds_bpermute_b32 v110, v209, v108
	s_cmp_lt_u32 s42, 32
	s_cselect_b64 vcc, -1, 0
	s_sub_i32 s2, s42, 31
	v_lshrrev_b32_e32 v0, s40, v102
	v_lshrrev_b32_e32 v111, s2, v103
	v_cndmask_b32_e32 v0, v111, v0, vcc
	v_and_b32_e32 v0, 1, v0
	s_waitcnt lgkmcnt(0)
	v_max_f32_e32 v108, v108, v110
	v_cmp_eq_u32_e64 s[2:3], 0, v0
	s_nop 1
	v_cndmask_b32_e64 v0, v108, v196, s[2:3]
	v_max_f32_e32 v116, v117, v0
	v_sub_f32_e32 v0, v117, v116
	v_exp_f32_e32 v108, v0
	s_nop 0
	v_cmp_neq_f32_e32 vcc, 1.0, v108
	s_cbranch_vccz .LBB0_1173
	v_pk_mul_f32 v[32:33], v[32:33], v[108:109] op_sel_hi:[1,0]
	v_pk_mul_f32 v[30:31], v[30:31], v[108:109] op_sel_hi:[1,0]
	v_pk_mul_f32 v[28:29], v[28:29], v[108:109] op_sel_hi:[1,0]
	v_pk_mul_f32 v[26:27], v[26:27], v[108:109] op_sel_hi:[1,0]
	v_pk_mul_f32 v[24:25], v[24:25], v[108:109] op_sel_hi:[1,0]
	v_pk_mul_f32 v[22:23], v[22:23], v[108:109] op_sel_hi:[1,0]
	v_pk_mul_f32 v[20:21], v[20:21], v[108:109] op_sel_hi:[1,0]
	v_pk_mul_f32 v[18:19], v[18:19], v[108:109] op_sel_hi:[1,0]
	v_pk_mul_f32 v[16:17], v[16:17], v[108:109] op_sel_hi:[1,0]
	v_pk_mul_f32 v[14:15], v[14:15], v[108:109] op_sel_hi:[1,0]
	v_pk_mul_f32 v[12:13], v[12:13], v[108:109] op_sel_hi:[1,0]
	v_pk_mul_f32 v[10:11], v[10:11], v[108:109] op_sel_hi:[1,0]
	v_pk_mul_f32 v[8:9], v[8:9], v[108:109] op_sel_hi:[1,0]
	v_pk_mul_f32 v[6:7], v[6:7], v[108:109] op_sel_hi:[1,0]
	v_pk_mul_f32 v[4:5], v[4:5], v[108:109] op_sel_hi:[1,0]
	v_pk_mul_f32 v[2:3], v[2:3], v[108:109] op_sel_hi:[1,0]

.LBB0_1188:
	v_max_f32_e32 v0, v34, v35
	v_max3_f32 v0, v0, v36, v37
	v_max3_f32 v0, v0, v38, v39
	v_max3_f32 v0, v0, v40, v41
	v_max3_f32 v0, v0, v42, v43
	v_max3_f32 v0, v0, v44, v45
	v_max3_f32 v0, v0, v46, v47
	v_max3_f32 v0, v0, v48, v49
	v_max3_f32 v0, v0, v50, v51
	v_max3_f32 v0, v0, v52, v53
	v_max3_f32 v0, v0, v54, v55
	v_max3_f32 v0, v0, v56, v57
	v_max3_f32 v0, v0, v58, v59
	v_max3_f32 v0, v0, v60, v61
	v_max3_f32 v0, v0, v62, v63
	v_max3_f32 v0, v0, v64, v65
	ds_bpermute_b32 v102, v209, v0
	s_waitcnt lgkmcnt(0)
	v_max3_f32 v108, v107, v0, v102
	v_sub_f32_e32 v0, v107, v108
	v_exp_f32_e32 v102, v0
	s_nop 0
	v_cmp_neq_f32_e32 vcc, 1.0, v102
	s_cbranch_vccz .LBB0_1190
	v_pk_mul_f32 v[16:17], v[16:17], v[102:103] op_sel_hi:[1,0]
	v_pk_mul_f32 v[14:15], v[14:15], v[102:103] op_sel_hi:[1,0]
	v_pk_mul_f32 v[12:13], v[12:13], v[102:103] op_sel_hi:[1,0]
	v_pk_mul_f32 v[10:11], v[10:11], v[102:103] op_sel_hi:[1,0]
	v_pk_mul_f32 v[8:9], v[8:9], v[102:103] op_sel_hi:[1,0]
	v_pk_mul_f32 v[6:7], v[6:7], v[102:103] op_sel_hi:[1,0]
	v_pk_mul_f32 v[4:5], v[4:5], v[102:103] op_sel_hi:[1,0]
	v_pk_mul_f32 v[2:3], v[2:3], v[102:103] op_sel_hi:[1,0]
	v_pk_mul_f32 v[32:33], v[32:33], v[102:103] op_sel_hi:[1,0]
	v_pk_mul_f32 v[30:31], v[30:31], v[102:103] op_sel_hi:[1,0]
	v_pk_mul_f32 v[28:29], v[28:29], v[102:103] op_sel_hi:[1,0]
	v_pk_mul_f32 v[26:27], v[26:27], v[102:103] op_sel_hi:[1,0]
	v_pk_mul_f32 v[24:25], v[24:25], v[102:103] op_sel_hi:[1,0]
	v_pk_mul_f32 v[22:23], v[22:23], v[102:103] op_sel_hi:[1,0]
	v_pk_mul_f32 v[20:21], v[20:21], v[102:103] op_sel_hi:[1,0]
	v_pk_mul_f32 v[18:19], v[18:19], v[102:103] op_sel_hi:[1,0]

.LBB0_1199:
	v_max_f32_e32 v0, v66, v67
	v_max3_f32 v0, v0, v68, v69
	v_max3_f32 v0, v0, v70, v71
	v_max3_f32 v0, v0, v72, v73
	v_max3_f32 v0, v0, v74, v75
	v_max3_f32 v0, v0, v76, v77
	v_max3_f32 v0, v0, v78, v79
	v_max3_f32 v0, v0, v80, v81
	v_max3_f32 v0, v0, v82, v83
	v_max3_f32 v0, v0, v84, v85
	v_max3_f32 v0, v0, v86, v87
	v_max3_f32 v0, v0, v88, v89
	v_max3_f32 v0, v0, v90, v91
	v_max3_f32 v0, v0, v92, v93
	v_max3_f32 v0, v0, v94, v95
	v_max3_f32 v0, v0, v96, v97
	ds_bpermute_b32 v102, v209, v0
	s_waitcnt lgkmcnt(0)
	v_max3_f32 v107, v108, v0, v102
	v_sub_f32_e32 v0, v108, v107
	v_exp_f32_e32 v102, v0
	s_nop 0
	v_cmp_neq_f32_e32 vcc, 1.0, v102
	s_cbranch_vccz .LBB0_1201
	v_pk_mul_f32 v[16:17], v[16:17], v[102:103] op_sel_hi:[1,0]
	v_pk_mul_f32 v[14:15], v[14:15], v[102:103] op_sel_hi:[1,0]
	v_pk_mul_f32 v[12:13], v[12:13], v[102:103] op_sel_hi:[1,0]
	v_pk_mul_f32 v[10:11], v[10:11], v[102:103] op_sel_hi:[1,0]
	v_pk_mul_f32 v[8:9], v[8:9], v[102:103] op_sel_hi:[1,0]
	v_pk_mul_f32 v[6:7], v[6:7], v[102:103] op_sel_hi:[1,0]
	v_pk_mul_f32 v[4:5], v[4:5], v[102:103] op_sel_hi:[1,0]
	v_pk_mul_f32 v[2:3], v[2:3], v[102:103] op_sel_hi:[1,0]
	v_pk_mul_f32 v[32:33], v[32:33], v[102:103] op_sel_hi:[1,0]
	v_pk_mul_f32 v[30:31], v[30:31], v[102:103] op_sel_hi:[1,0]
	v_pk_mul_f32 v[28:29], v[28:29], v[102:103] op_sel_hi:[1,0]
	v_pk_mul_f32 v[26:27], v[26:27], v[102:103] op_sel_hi:[1,0]
	v_pk_mul_f32 v[24:25], v[24:25], v[102:103] op_sel_hi:[1,0]
	v_pk_mul_f32 v[22:23], v[22:23], v[102:103] op_sel_hi:[1,0]
	v_pk_mul_f32 v[20:21], v[20:21], v[102:103] op_sel_hi:[1,0]
	v_pk_mul_f32 v[18:19], v[18:19], v[102:103] op_sel_hi:[1,0]
